# gdn scan: first four chunks use exact counted waits instead of a full drain after priming the ring
# baseline (speedup 1.0000x reference)
; __device__ __forceinline__ unsigned xb_ld(unsigned* p)              { return __hip_atomic_load(p, __ATOMIC_RELAXED, __HIP_MEMORY_SCOPE_AGENT); }
; #define XB_SPIN(cond, bar) do { unsigned _sp = 0; while (cond) { __builtin_amdgcn_s_sleep(1); \
;     if ((++_sp & 255u) == 0u) { if (xb_ld(&(bar)[XB_TMO])) break; if (_sp > XB_SPIN_CAP) { atomicAdd(&(bar)[XB_TMO], 1u); break; } } } } while (0)
; __device__ __forceinline__ void xcd_barrier(const XcdBarrier& b) {
;     ...
;             asm volatile("s_waitcnt vmcnt(0)" ::: "memory");
;         } else {
;             XB_SPIN(xb_ld(&bar[XB_XGEN(b.x)]) == gen, bar);
;             __builtin_amdgcn_fence(__ATOMIC_ACQUIRE, "agent");
;             asm volatile("s_waitcnt vmcnt(0)" ::: "memory");
;         }
;     }
;     __syncthreads();
; __global__ void __launch_bounds__(512, 2) fwd_kernel(Ctx X) {
;     ...
;         int tz = tid; asm volatile("" : "+v"(tz));
;         for (int i = blockIdx.x * 512 + tz; i < M; i += G * 512) { WSP(float, WS_RSA)[i] = 0.f; WSP(float, WS_RSB)[i] = 0.f; }
.Lgs0_done:
	s_waitcnt vmcnt(0)
	s_branch .Lgs0_pad
	s_nop 0
	s_nop 0
	s_nop 0
	s_nop 0
	s_nop 0
	s_nop 0
	s_nop 0
	s_nop 0
	s_nop 0
	s_nop 0
	s_nop 0
	s_nop 0
	s_nop 0
	s_nop 0
	s_nop 0
	s_nop 0
	s_nop 0
	s_nop 0
	s_nop 0
	s_nop 0
	s_nop 0
	s_nop 0
	s_nop 0
	s_nop 0
	s_nop 0
	s_nop 0
	s_nop 0
	s_nop 0
	s_nop 0
	s_nop 0
	s_nop 0
	s_nop 0
	s_nop 0
	s_nop 0
	s_nop 0
	s_nop 0
	s_nop 0
	s_nop 0
	s_nop 0
	s_nop 0
	s_nop 0
	s_nop 0
	s_nop 0
	s_nop 0
	s_nop 0
	s_nop 0
	s_nop 0
	s_nop 0
	s_nop 0
	s_nop 0
	s_nop 0
	s_nop 0
	s_nop 0
	s_nop 0
	s_nop 0
	s_nop 0
	s_nop 0
	s_nop 0
	s_nop 0
	s_nop 0
	s_nop 0
	s_nop 0
	s_nop 0
	s_nop 0
	s_nop 0
	s_nop 0
	s_nop 0
	s_nop 0
	s_nop 0
	s_nop 0
	s_nop 0
	s_nop 0
	s_nop 0
	s_nop 0
	s_nop 0
	s_nop 0
	s_nop 0
	s_nop 0
	s_nop 0
	s_nop 0
	s_nop 0
	s_nop 0
	s_nop 0
	s_nop 0
	s_nop 0
	s_nop 0
	s_nop 0
	s_nop 0
	s_nop 0
	s_nop 0
	s_nop 0
	s_nop 0
	s_nop 0
	s_nop 0
	s_nop 0
	s_nop 0
	s_nop 0
	s_nop 0
	s_nop 0
	s_nop 0
	s_nop 0
	s_nop 0
	s_nop 0
	s_nop 0
	s_nop 0
	s_nop 0
	s_nop 0
	s_nop 0
	s_nop 0
	s_nop 0
	s_nop 0
	s_nop 0
	s_nop 0
	s_nop 0
	s_nop 0
	s_nop 0
	s_nop 0
	s_nop 0
	s_nop 0
	s_nop 0
	s_nop 0
	s_nop 0
	s_nop 0
	s_nop 0
	s_nop 0
	s_nop 0
	s_nop 0
	s_nop 0
	s_nop 0
	s_nop 0
	s_nop 0
	s_nop 0
	s_nop 0
	s_nop 0
	s_nop 0
	s_nop 0
	s_nop 0
	s_nop 0
	s_nop 0
	s_nop 0
	s_nop 0
	s_nop 0
	s_nop 0
	s_nop 0
	s_nop 0
	s_nop 0
	s_nop 0
	s_nop 0
.Lgs0_pad:
.LBB0_228:
	s_or_b64 exec, exec, s[0:1]
	s_xor_b64 s[0:1], s[26:27], -1
	v_writelane_b32 v255, s0, 30
	s_waitcnt lgkmcnt(0)
	v_mov_b32_e32 v6, v224
	v_writelane_b32 v255, s1, 31
	s_barrier
	v_readlane_b32 s0, v255, 1
	s_nop 1
	v_add_u32_e32 v6, s0, v6
	s_mov_b32 s0, 0x8000
	v_cmp_gt_i32_e32 vcc, s0, v6
	s_and_saveexec_b64 s[0:1], vcc
	s_cbranch_execz .LBB0_231
	v_ashrrev_i32_e32 v7, 31, v6
	v_lshl_add_u64 v[8:9], v[6:7], 2, s[72:73]
	s_mov_b64 s[4:5], 0

; #define SCAN_LOAD_D(slot, cc) { const int c_ = (cc) < NCH ? (cc) : NCH - 1; const bf16_t* bcn = bc0 + (size_t)c_ * 4096; \
;             _Pragma("unroll") for (int t = 0; t < 4; ++t) { cb[slot][t] = *(const u32x2*)(bcn + 256 * t); cm[slot][t] = mixer == 2 ? *(const f32x4*)(mv0 + (size_t)c_ * 64 + 16 * t) : (f32x4){g64, g64, g64, g64}; } }
; __device__ __forceinline__ void scan_phase(const Ctx& X, int wave, int lane) {
;     const int job = blockIdx.x;
;     if (job >= 192 || wave != 0) return;
;     asm volatile("" : "+v"(lane));
;     const int mixer = job >> 6, rem = job & 63, bh = rem >> 2, vg = rem & 3;
;     const int uid0 = (mixer * 16 + bh) * NCH;
;     const int r = lane & 15, q = lane >> 4;
;     bf16_t* bc0 = WSP(bf16_t, WS_BCS) + (size_t)uid0 * 4096 + (vg * 4 * 64 + lane) * 4;
;     float S[4][4];
; #pragma unroll
;     for (int t = 0; t < 4; ++t)
; #pragma unroll
;         for (int j = 0; j < 4; ++j) S[t][j] = 0.f;
;     ...
;         const int h = bh & 3;
;         const float g64 = __expf(64.0f * log1pf(-exp2f(-5.0f - (float)h)));
;         const float* mv0 = WSP(const float, WS_MVEC) + (size_t)(mixer == 2 ? uid0 - 2 * 2048 : 0) * 64 + 4 * q;
;         u32x2 cb[4][4]; f32x4 cm[4][4];
;     ...
;         SCAN_LOAD_D(0, 0) SCAN_LOAD_D(1, 1) SCAN_LOAD_D(2, 2)
.Lgs1_done:
	s_waitcnt vmcnt(0)
	s_branch .Lgs1_pad
	s_nop 0
.Lgs1_pad:
.LBB0_675:
	s_or_b64 exec, exec, s[0:1]
	v_readlane_b32 s0, v253, 7
	v_readlane_b32 s1, v253, 8
	s_andn2_b64 vcc, exec, s[0:1]
	s_waitcnt lgkmcnt(0)
	s_barrier
	s_cbranch_vccnz .LBB0_739
	v_mov_b32_e32 v155, v232
	v_readlane_b32 s0, v253, 9
	v_readlane_b32 s4, v253, 14
	v_readlane_b32 s5, v253, 15
	v_add_lshl_u32 v86, v155, s0, 2
	v_readlane_b32 s0, v253, 12
	v_ashrrev_i32_e32 v87, 31, v86
	v_readlane_b32 s1, v253, 13
	s_and_b64 vcc, exec, s[4:5]
	s_nop 0
	v_lshl_add_u64 v[162:163], v[86:87], 1, s[0:1]
	s_mov_b64 s[0:1], -1
	s_cbranch_vccz .LBB0_736
	s_lshr_b32 s99, s2, 6
	s_and_b32 s20, s2, 63
	s_lshr_b32 s21, s20, 2
	s_and_b32 s20, s20, 3
	s_lshl_b32 s25, s99, 4
	s_add_i32 s25, s25, s21
	s_lshl_b32 s25, s25, 20
	s_lshl_b32 s20, s20, 11
	s_add_u32 s44, s30, 0x3500000
	s_addc_u32 s45, s31, 0
	s_add_u32 s44, s44, s25
	s_addc_u32 s45, s45, 0
	s_add_u32 s44, s44, s20
	s_addc_u32 s45, s45, 0
	s_lshl_b32 s21, s21, 15
	s_add_u32 s46, s30, 0x1f600000
	s_addc_u32 s47, s31, 0
	s_add_u32 s46, s46, s21
	s_addc_u32 s47, s47, 0
	v_lshlrev_b32_e32 v6, 3, v155
	v_lshrrev_b32_e32 v7, 4, v155
	v_lshlrev_b32_e32 v7, 4, v7
	v_mov_b32_e32 v8, 0
	v_mov_b32_e32 v9, 0
	v_mov_b32_e32 v10, 0
	v_mov_b32_e32 v11, 0
	v_mov_b32_e32 v12, 0
	v_mov_b32_e32 v13, 0
	v_mov_b32_e32 v14, 0
	v_mov_b32_e32 v15, 0
	v_mov_b32_e32 v16, 0
	v_mov_b32_e32 v17, 0
	v_mov_b32_e32 v18, 0
	v_mov_b32_e32 v19, 0
	v_mov_b32_e32 v20, 0
	v_mov_b32_e32 v21, 0
	v_mov_b32_e32 v22, 0
	v_mov_b32_e32 v23, 0
	s_cmp_eq_u32 s99, 2
	s_cbranch_scc1 .Lsd2_start

; __device__ __forceinline__ void scan_phase(const Ctx& X, int wave, int lane) {
;     const int job = blockIdx.x;
;     if (job >= 192 || wave != 0) return;
;     asm volatile("" : "+v"(lane));
;     const int mixer = job >> 6, rem = job & 63, bh = rem >> 2, vg = rem & 3;
;     const int uid0 = (mixer * 16 + bh) * NCH;
;     const int r = lane & 15, q = lane >> 4;
;     bf16_t* bc0 = WSP(bf16_t, WS_BCS) + (size_t)uid0 * 4096 + (vg * 4 * 64 + lane) * 4;
;     float S[4][4];
; #pragma unroll
;     for (int t = 0; t < 4; ++t)
; #pragma unroll
;         for (int j = 0; j < 4; ++j) S[t][j] = 0.f;
;     if (mixer == 1) {
;         const bf16_t* mm0 = WSP(const bf16_t, WS_MM) + (size_t)(uid0 - 2048) * 4096;
;         u32x2 cb[4][4], ca[4][4][2][2];
;     ...
;         SCAN_LOAD_G(0, 0) SCAN_LOAD_G(1, 1) SCAN_LOAD_G(2, 2)
.LBB0_736:
	s_and_b64 vcc, exec, s[0:1]
	s_cbranch_vccz .LBB0_739
	s_and_b32 s20, s2, 63
	s_lshr_b32 s21, s20, 2
	s_and_b32 s20, s20, 3
	s_add_i32 s25, s21, 16
	s_lshl_b32 s25, s25, 20
	s_lshl_b32 s20, s20, 11
	s_add_u32 s44, s30, 0x3500000
	s_addc_u32 s45, s31, 0
	s_add_u32 s44, s44, s25
	s_addc_u32 s45, s45, 0
	s_add_u32 s44, s44, s20
	s_addc_u32 s45, s45, 0
	s_add_u32 s46, s30, 0x5500000
	s_addc_u32 s47, s31, 0
	s_add_u32 s46, s46, s25
	s_addc_u32 s47, s47, 0
	v_lshlrev_b32_e32 v6, 3, v155
	v_lshlrev_b32_e32 v7, 4, v155
	v_add_u32_e32 v129, 0x1000, v7
	v_mov_b32_e32 v8, 0
	v_mov_b32_e32 v9, 0
	v_mov_b32_e32 v10, 0
	v_mov_b32_e32 v11, 0
	v_mov_b32_e32 v12, 0
	v_mov_b32_e32 v13, 0
	v_mov_b32_e32 v14, 0
	v_mov_b32_e32 v15, 0
	v_mov_b32_e32 v16, 0
	v_mov_b32_e32 v17, 0
	v_mov_b32_e32 v18, 0
	v_mov_b32_e32 v19, 0
	v_mov_b32_e32 v20, 0
	v_mov_b32_e32 v21, 0
	v_mov_b32_e32 v22, 0
	v_mov_b32_e32 v23, 0
	s_mov_b32 s39, 0
	s_add_i32 s37, s39, 0
	s_min_u32 s37, s37, 0x7f
	s_lshl_b32 s38, s37, 13
	s_add_u32 s82, s44, s38
	s_addc_u32 s83, s45, 0
	global_load_dwordx2 v[24:25], v6, s[82:83]
	global_load_dwordx2 v[26:27], v6, s[82:83] offset:512
	global_load_dwordx2 v[28:29], v6, s[82:83] offset:1024
	global_load_dwordx2 v[30:31], v6, s[82:83] offset:1536
	s_add_u32 s82, s46, s38
	s_addc_u32 s83, s47, 0
	global_load_dwordx4 v[56:59], v7, s[82:83]
	global_load_dwordx4 v[60:63], v7, s[82:83] offset:1024
	global_load_dwordx4 v[64:67], v7, s[82:83] offset:2048
	global_load_dwordx4 v[68:71], v7, s[82:83] offset:3072
	global_load_dwordx4 v[72:75], v129, s[82:83]
	global_load_dwordx4 v[76:79], v129, s[82:83] offset:1024
	global_load_dwordx4 v[80:83], v129, s[82:83] offset:2048
	global_load_dwordx4 v[84:87], v129, s[82:83] offset:3072
	s_add_i32 s37, s39, 1
	s_min_u32 s37, s37, 0x7f
	s_lshl_b32 s38, s37, 13
	s_add_u32 s82, s44, s38
	s_addc_u32 s83, s45, 0
	global_load_dwordx2 v[32:33], v6, s[82:83]
	global_load_dwordx2 v[34:35], v6, s[82:83] offset:512
	global_load_dwordx2 v[36:37], v6, s[82:83] offset:1024
	global_load_dwordx2 v[38:39], v6, s[82:83] offset:1536
	s_add_u32 s82, s46, s38
	s_addc_u32 s83, s47, 0
	global_load_dwordx4 v[88:91], v7, s[82:83]
	global_load_dwordx4 v[92:95], v7, s[82:83] offset:1024
	global_load_dwordx4 v[96:99], v7, s[82:83] offset:2048
	global_load_dwordx4 v[100:103], v7, s[82:83] offset:3072
	global_load_dwordx4 v[104:107], v129, s[82:83]
	global_load_dwordx4 v[108:111], v129, s[82:83] offset:1024
	global_load_dwordx4 v[112:115], v129, s[82:83] offset:2048
	global_load_dwordx4 v[116:119], v129, s[82:83] offset:3072
	s_add_i32 s37, s39, 2
	s_min_u32 s37, s37, 0x7f
	s_lshl_b32 s38, s37, 13
	s_add_u32 s82, s44, s38
	s_addc_u32 s83, s45, 0
	global_load_dwordx2 v[40:41], v6, s[82:83]
	global_load_dwordx2 v[42:43], v6, s[82:83] offset:512
	global_load_dwordx2 v[44:45], v6, s[82:83] offset:1024
	global_load_dwordx2 v[46:47], v6, s[82:83] offset:1536
	s_add_u32 s82, s46, s38
	s_addc_u32 s83, s47, 0
	global_load_dwordx4 v[132:135], v7, s[82:83]
	global_load_dwordx4 v[136:139], v7, s[82:83] offset:1024
	global_load_dwordx4 v[140:143], v7, s[82:83] offset:2048
	global_load_dwordx4 v[144:147], v7, s[82:83] offset:3072
	global_load_dwordx4 v[148:151], v129, s[82:83]
	global_load_dwordx4 v[164:167], v129, s[82:83] offset:1024
	global_load_dwordx4 v[168:171], v129, s[82:83] offset:2048
	global_load_dwordx4 v[172:175], v129, s[82:83] offset:3072
	s_add_i32 s37, s39, 3
	s_min_u32 s37, s37, 0x7f
	s_lshl_b32 s38, s37, 13
	s_add_u32 s82, s44, s38
	s_addc_u32 s83, s45, 0
	global_load_dwordx2 v[48:49], v6, s[82:83]
	global_load_dwordx2 v[50:51], v6, s[82:83] offset:512
	global_load_dwordx2 v[52:53], v6, s[82:83] offset:1024
	global_load_dwordx2 v[54:55], v6, s[82:83] offset:1536
	s_add_u32 s82, s46, s38
	s_addc_u32 s83, s47, 0
	global_load_dwordx4 v[176:179], v7, s[82:83]
	global_load_dwordx4 v[184:187], v7, s[82:83] offset:1024
	global_load_dwordx4 v[188:191], v7, s[82:83] offset:2048
	global_load_dwordx4 v[192:195], v7, s[82:83] offset:3072
	global_load_dwordx4 v[196:199], v129, s[82:83]
	global_load_dwordx4 v[200:203], v129, s[82:83] offset:1024
	global_load_dwordx4 v[204:207], v129, s[82:83] offset:2048
	global_load_dwordx4 v[208:211], v129, s[82:83] offset:3072
	s_waitcnt vmcnt(44)
	v_cvt_pk_bf16_f32 v120, v8, v9
	v_cvt_pk_bf16_f32 v121, v10, v11
	v_cvt_pk_bf16_f32 v122, v12, v13
	v_cvt_pk_bf16_f32 v123, v14, v15
	v_cvt_pk_bf16_f32 v124, v16, v17
	v_cvt_pk_bf16_f32 v125, v18, v19
	v_cvt_pk_bf16_f32 v126, v20, v21
	v_cvt_pk_bf16_f32 v127, v22, v23
	s_add_i32 s37, s39, 0
	s_lshl_b32 s38, s37, 13
	s_add_u32 s40, s44, s38
	s_addc_u32 s41, s45, 0
	global_store_dwordx2 v6, v[120:121], s[40:41]
	global_store_dwordx2 v6, v[122:123], s[40:41] offset:512
	global_store_dwordx2 v6, v[124:125], s[40:41] offset:1024
	global_store_dwordx2 v6, v[126:127], s[40:41] offset:1536
	v_lshlrev_b32_e32 v8, 16, v24
	v_and_b32_e32 v9, 0xffff0000, v24
	v_lshlrev_b32_e32 v10, 16, v25
	v_and_b32_e32 v11, 0xffff0000, v25
	v_lshlrev_b32_e32 v12, 16, v26
	v_and_b32_e32 v13, 0xffff0000, v26
	v_lshlrev_b32_e32 v14, 16, v27
	v_and_b32_e32 v15, 0xffff0000, v27
	v_lshlrev_b32_e32 v16, 16, v28
	v_and_b32_e32 v17, 0xffff0000, v28
	v_lshlrev_b32_e32 v18, 16, v29
	v_and_b32_e32 v19, 0xffff0000, v29
	v_lshlrev_b32_e32 v20, 16, v30
	v_and_b32_e32 v21, 0xffff0000, v30
	v_lshlrev_b32_e32 v22, 16, v31
	v_and_b32_e32 v23, 0xffff0000, v31
	s_waitcnt vmcnt(40)
; __device__ __forceinline__ float bf_lo(unsigned u) { return __uint_as_float(u << 16); }
; __device__ __forceinline__ float bf_hi(unsigned u) { return __uint_as_float(u & 0xffff0000u); }
; __device__ __forceinline__ unsigned pk2(float lo, float hi) { return pg8::cvt_pk_bf16(lo, hi); }
; __device__ __forceinline__ void scan_phase(const Ctx& X, int wave, int lane) {
;     ...
;         for (int c0 = 0; c0 < NCH; c0 += 4) {
; #pragma unroll
;             for (int k = 0; k < 4; ++k) {
;                 const int c = c0 + k;
;                 SCAN_LOAD_G((k + 3) & 3, c + 3)
;                 bf16_t* bcc = bc0 + (size_t)c * 4096;
;                 u32x2 sp[4];
; #pragma unroll
;                 for (int t = 0; t < 4; ++t) { sp[t].x = pk2(S[t][0], S[t][1]); sp[t].y = pk2(S[t][2], S[t][3]);
;                     asm volatile("" : "+v"(sp[t].x) : "v"(cb[k][t].x));
;                     *(u32x2*)(bcc + 256 * t) = sp[t]; }
;                 bf16x8 bfr[2];
; #pragma unroll
;                 for (int s2 = 0; s2 < 2; ++s2) { u32x4 w; w.x = sp[2 * s2].x; w.y = sp[2 * s2].y; w.z = sp[2 * s2 + 1].x; w.w = sp[2 * s2 + 1].y; bfr[s2] = __builtin_bit_cast(bf16x8, w); }
; #pragma unroll
;                 for (int t = 0; t < 4; ++t) {
;                     f32x4 acc = (f32x4){bf_lo(cb[k][t].x), bf_hi(cb[k][t].x), bf_lo(cb[k][t].y), bf_hi(cb[k][t].y)};
; #pragma unroll
;                     for (int s2 = 0; s2 < 2; ++s2) { u32x4 w; w.x = ca[k][t][s2][0].x; w.y = ca[k][t][s2][0].y; w.z = ca[k][t][s2][1].x; w.w = ca[k][t][s2][1].y;
;                         acc = __builtin_amdgcn_mfma_f32_16x16x32_bf16(__builtin_bit_cast(bf16x8, w), bfr[s2], acc, 0, 0, 0); }
;                     S[t][0] = acc[0]; S[t][1] = acc[1]; S[t][2] = acc[2]; S[t][3] = acc[3];
;                 }
;             }
;         }
	v_mfma_f32_16x16x32_bf16 v[8:11], v[56:59], v[120:123], v[8:11]
	v_mfma_f32_16x16x32_bf16 v[12:15], v[64:67], v[120:123], v[12:15]
	v_mfma_f32_16x16x32_bf16 v[16:19], v[72:75], v[120:123], v[16:19]
	v_mfma_f32_16x16x32_bf16 v[20:23], v[80:83], v[120:123], v[20:23]
	v_mfma_f32_16x16x32_bf16 v[8:11], v[60:63], v[124:127], v[8:11]
	v_mfma_f32_16x16x32_bf16 v[12:15], v[68:71], v[124:127], v[12:15]
	v_mfma_f32_16x16x32_bf16 v[16:19], v[76:79], v[124:127], v[16:19]
	v_mfma_f32_16x16x32_bf16 v[20:23], v[84:87], v[124:127], v[20:23]
	s_add_i32 s37, s39, 4
	s_min_u32 s37, s37, 0x7f
	s_lshl_b32 s38, s37, 13
	s_add_u32 s82, s44, s38
	s_addc_u32 s83, s45, 0
	global_load_dwordx2 v[24:25], v6, s[82:83]
	global_load_dwordx2 v[26:27], v6, s[82:83] offset:512
	global_load_dwordx2 v[28:29], v6, s[82:83] offset:1024
	global_load_dwordx2 v[30:31], v6, s[82:83] offset:1536
	s_add_u32 s82, s46, s38
	s_addc_u32 s83, s47, 0
	global_load_dwordx4 v[56:59], v7, s[82:83]
	global_load_dwordx4 v[60:63], v7, s[82:83] offset:1024
	global_load_dwordx4 v[64:67], v7, s[82:83] offset:2048
	global_load_dwordx4 v[68:71], v7, s[82:83] offset:3072
	global_load_dwordx4 v[72:75], v129, s[82:83]
	global_load_dwordx4 v[76:79], v129, s[82:83] offset:1024
	global_load_dwordx4 v[80:83], v129, s[82:83] offset:2048
	global_load_dwordx4 v[84:87], v129, s[82:83] offset:3072
	s_waitcnt vmcnt(48)
	v_cvt_pk_bf16_f32 v120, v8, v9
	v_cvt_pk_bf16_f32 v121, v10, v11
	v_cvt_pk_bf16_f32 v122, v12, v13
	v_cvt_pk_bf16_f32 v123, v14, v15
	v_cvt_pk_bf16_f32 v124, v16, v17
	v_cvt_pk_bf16_f32 v125, v18, v19
	v_cvt_pk_bf16_f32 v126, v20, v21
	v_cvt_pk_bf16_f32 v127, v22, v23
	s_add_i32 s37, s39, 1
	s_lshl_b32 s38, s37, 13
	s_add_u32 s40, s44, s38
	s_addc_u32 s41, s45, 0
	global_store_dwordx2 v6, v[120:121], s[40:41]
	global_store_dwordx2 v6, v[122:123], s[40:41] offset:512
	global_store_dwordx2 v6, v[124:125], s[40:41] offset:1024
	global_store_dwordx2 v6, v[126:127], s[40:41] offset:1536
	v_lshlrev_b32_e32 v8, 16, v32
	v_and_b32_e32 v9, 0xffff0000, v32
	v_lshlrev_b32_e32 v10, 16, v33
	v_and_b32_e32 v11, 0xffff0000, v33
	v_lshlrev_b32_e32 v12, 16, v34
	v_and_b32_e32 v13, 0xffff0000, v34
	v_lshlrev_b32_e32 v14, 16, v35
	v_and_b32_e32 v15, 0xffff0000, v35
	v_lshlrev_b32_e32 v16, 16, v36
	v_and_b32_e32 v17, 0xffff0000, v36
	v_lshlrev_b32_e32 v18, 16, v37
	v_and_b32_e32 v19, 0xffff0000, v37
	v_lshlrev_b32_e32 v20, 16, v38
	v_and_b32_e32 v21, 0xffff0000, v38
	v_lshlrev_b32_e32 v22, 16, v39
	v_and_b32_e32 v23, 0xffff0000, v39
	s_waitcnt vmcnt(44)
	v_mfma_f32_16x16x32_bf16 v[8:11], v[88:91], v[120:123], v[8:11]
	v_mfma_f32_16x16x32_bf16 v[12:15], v[96:99], v[120:123], v[12:15]
	v_mfma_f32_16x16x32_bf16 v[16:19], v[104:107], v[120:123], v[16:19]
	v_mfma_f32_16x16x32_bf16 v[20:23], v[112:115], v[120:123], v[20:23]
	v_mfma_f32_16x16x32_bf16 v[8:11], v[92:95], v[124:127], v[8:11]
	v_mfma_f32_16x16x32_bf16 v[12:15], v[100:103], v[124:127], v[12:15]
	v_mfma_f32_16x16x32_bf16 v[16:19], v[108:111], v[124:127], v[16:19]
	v_mfma_f32_16x16x32_bf16 v[20:23], v[116:119], v[124:127], v[20:23]
	s_add_i32 s37, s39, 5
	s_min_u32 s37, s37, 0x7f
	s_lshl_b32 s38, s37, 13
	s_add_u32 s82, s44, s38
	s_addc_u32 s83, s45, 0
	global_load_dwordx2 v[32:33], v6, s[82:83]
	global_load_dwordx2 v[34:35], v6, s[82:83] offset:512
	global_load_dwordx2 v[36:37], v6, s[82:83] offset:1024
	global_load_dwordx2 v[38:39], v6, s[82:83] offset:1536
	s_add_u32 s82, s46, s38
	s_addc_u32 s83, s47, 0
	global_load_dwordx4 v[88:91], v7, s[82:83]
	global_load_dwordx4 v[92:95], v7, s[82:83] offset:1024
	global_load_dwordx4 v[96:99], v7, s[82:83] offset:2048
	global_load_dwordx4 v[100:103], v7, s[82:83] offset:3072
	global_load_dwordx4 v[104:107], v129, s[82:83]
	global_load_dwordx4 v[108:111], v129, s[82:83] offset:1024
	global_load_dwordx4 v[112:115], v129, s[82:83] offset:2048
	global_load_dwordx4 v[116:119], v129, s[82:83] offset:3072
	s_waitcnt vmcnt(52)
; __device__ __forceinline__ float bf_lo(unsigned u) { return __uint_as_float(u << 16); }
; __device__ __forceinline__ float bf_hi(unsigned u) { return __uint_as_float(u & 0xffff0000u); }
; __device__ __forceinline__ unsigned pk2(float lo, float hi) { return pg8::cvt_pk_bf16(lo, hi); }
; __device__ __forceinline__ void scan_phase(const Ctx& X, int wave, int lane) {
;     ...
;         for (int c0 = 0; c0 < NCH; c0 += 4) {
; #pragma unroll
;             for (int k = 0; k < 4; ++k) {
;                 const int c = c0 + k;
;                 SCAN_LOAD_G((k + 3) & 3, c + 3)
;                 bf16_t* bcc = bc0 + (size_t)c * 4096;
;                 u32x2 sp[4];
; #pragma unroll
;                 for (int t = 0; t < 4; ++t) { sp[t].x = pk2(S[t][0], S[t][1]); sp[t].y = pk2(S[t][2], S[t][3]);
;                     asm volatile("" : "+v"(sp[t].x) : "v"(cb[k][t].x));
;                     *(u32x2*)(bcc + 256 * t) = sp[t]; }
;                 bf16x8 bfr[2];
; #pragma unroll
;                 for (int s2 = 0; s2 < 2; ++s2) { u32x4 w; w.x = sp[2 * s2].x; w.y = sp[2 * s2].y; w.z = sp[2 * s2 + 1].x; w.w = sp[2 * s2 + 1].y; bfr[s2] = __builtin_bit_cast(bf16x8, w); }
; #pragma unroll
;                 for (int t = 0; t < 4; ++t) {
;                     f32x4 acc = (f32x4){bf_lo(cb[k][t].x), bf_hi(cb[k][t].x), bf_lo(cb[k][t].y), bf_hi(cb[k][t].y)};
; #pragma unroll
;                     for (int s2 = 0; s2 < 2; ++s2) { u32x4 w; w.x = ca[k][t][s2][0].x; w.y = ca[k][t][s2][0].y; w.z = ca[k][t][s2][1].x; w.w = ca[k][t][s2][1].y;
;                         acc = __builtin_amdgcn_mfma_f32_16x16x32_bf16(__builtin_bit_cast(bf16x8, w), bfr[s2], acc, 0, 0, 0); }
;                     S[t][0] = acc[0]; S[t][1] = acc[1]; S[t][2] = acc[2]; S[t][3] = acc[3];
;                 }
;             }
;         }
	v_cvt_pk_bf16_f32 v120, v8, v9
	v_cvt_pk_bf16_f32 v121, v10, v11
	v_cvt_pk_bf16_f32 v122, v12, v13
	v_cvt_pk_bf16_f32 v123, v14, v15
	v_cvt_pk_bf16_f32 v124, v16, v17
	v_cvt_pk_bf16_f32 v125, v18, v19
	v_cvt_pk_bf16_f32 v126, v20, v21
	v_cvt_pk_bf16_f32 v127, v22, v23
	s_add_i32 s37, s39, 2
	s_lshl_b32 s38, s37, 13
	s_add_u32 s40, s44, s38
	s_addc_u32 s41, s45, 0
	global_store_dwordx2 v6, v[120:121], s[40:41]
	global_store_dwordx2 v6, v[122:123], s[40:41] offset:512
	global_store_dwordx2 v6, v[124:125], s[40:41] offset:1024
	global_store_dwordx2 v6, v[126:127], s[40:41] offset:1536
	v_lshlrev_b32_e32 v8, 16, v40
	v_and_b32_e32 v9, 0xffff0000, v40
	v_lshlrev_b32_e32 v10, 16, v41
	v_and_b32_e32 v11, 0xffff0000, v41
	v_lshlrev_b32_e32 v12, 16, v42
	v_and_b32_e32 v13, 0xffff0000, v42
	v_lshlrev_b32_e32 v14, 16, v43
	v_and_b32_e32 v15, 0xffff0000, v43
	v_lshlrev_b32_e32 v16, 16, v44
	v_and_b32_e32 v17, 0xffff0000, v44
	v_lshlrev_b32_e32 v18, 16, v45
	v_and_b32_e32 v19, 0xffff0000, v45
	v_lshlrev_b32_e32 v20, 16, v46
	v_and_b32_e32 v21, 0xffff0000, v46
	v_lshlrev_b32_e32 v22, 16, v47
	v_and_b32_e32 v23, 0xffff0000, v47
	s_waitcnt vmcnt(48)
	v_mfma_f32_16x16x32_bf16 v[8:11], v[132:135], v[120:123], v[8:11]
	v_mfma_f32_16x16x32_bf16 v[12:15], v[140:143], v[120:123], v[12:15]
	v_mfma_f32_16x16x32_bf16 v[16:19], v[148:151], v[120:123], v[16:19]
	v_mfma_f32_16x16x32_bf16 v[20:23], v[168:171], v[120:123], v[20:23]
	v_mfma_f32_16x16x32_bf16 v[8:11], v[136:139], v[124:127], v[8:11]
	v_mfma_f32_16x16x32_bf16 v[12:15], v[144:147], v[124:127], v[12:15]
	v_mfma_f32_16x16x32_bf16 v[16:19], v[164:167], v[124:127], v[16:19]
	v_mfma_f32_16x16x32_bf16 v[20:23], v[172:175], v[124:127], v[20:23]
	s_add_i32 s37, s39, 6
	s_min_u32 s37, s37, 0x7f
	s_lshl_b32 s38, s37, 13
	s_add_u32 s82, s44, s38
	s_addc_u32 s83, s45, 0
	global_load_dwordx2 v[40:41], v6, s[82:83]
	global_load_dwordx2 v[42:43], v6, s[82:83] offset:512
	global_load_dwordx2 v[44:45], v6, s[82:83] offset:1024
	global_load_dwordx2 v[46:47], v6, s[82:83] offset:1536
	s_add_u32 s82, s46, s38
	s_addc_u32 s83, s47, 0
	global_load_dwordx4 v[132:135], v7, s[82:83]
	global_load_dwordx4 v[136:139], v7, s[82:83] offset:1024
	global_load_dwordx4 v[140:143], v7, s[82:83] offset:2048
	global_load_dwordx4 v[144:147], v7, s[82:83] offset:3072
	global_load_dwordx4 v[148:151], v129, s[82:83]
	global_load_dwordx4 v[164:167], v129, s[82:83] offset:1024
	global_load_dwordx4 v[168:171], v129, s[82:83] offset:2048
	global_load_dwordx4 v[172:175], v129, s[82:83] offset:3072
	s_waitcnt vmcnt(56)
	v_cvt_pk_bf16_f32 v120, v8, v9
	v_cvt_pk_bf16_f32 v121, v10, v11
	v_cvt_pk_bf16_f32 v122, v12, v13
	v_cvt_pk_bf16_f32 v123, v14, v15
	v_cvt_pk_bf16_f32 v124, v16, v17
	v_cvt_pk_bf16_f32 v125, v18, v19
	v_cvt_pk_bf16_f32 v126, v20, v21
	v_cvt_pk_bf16_f32 v127, v22, v23
	s_add_i32 s37, s39, 3
	s_lshl_b32 s38, s37, 13
	s_add_u32 s40, s44, s38
	s_addc_u32 s41, s45, 0
	global_store_dwordx2 v6, v[120:121], s[40:41]
	global_store_dwordx2 v6, v[122:123], s[40:41] offset:512
	global_store_dwordx2 v6, v[124:125], s[40:41] offset:1024
	global_store_dwordx2 v6, v[126:127], s[40:41] offset:1536
	v_lshlrev_b32_e32 v8, 16, v48
	v_and_b32_e32 v9, 0xffff0000, v48
	v_lshlrev_b32_e32 v10, 16, v49
	v_and_b32_e32 v11, 0xffff0000, v49
	v_lshlrev_b32_e32 v12, 16, v50
	v_and_b32_e32 v13, 0xffff0000, v50
	v_lshlrev_b32_e32 v14, 16, v51
	v_and_b32_e32 v15, 0xffff0000, v51
	v_lshlrev_b32_e32 v16, 16, v52
	v_and_b32_e32 v17, 0xffff0000, v52
	v_lshlrev_b32_e32 v18, 16, v53
	v_and_b32_e32 v19, 0xffff0000, v53
	v_lshlrev_b32_e32 v20, 16, v54
	v_and_b32_e32 v21, 0xffff0000, v54
	v_lshlrev_b32_e32 v22, 16, v55
	v_and_b32_e32 v23, 0xffff0000, v55
	s_waitcnt vmcnt(52)
	v_mfma_f32_16x16x32_bf16 v[8:11], v[176:179], v[120:123], v[8:11]
	v_mfma_f32_16x16x32_bf16 v[12:15], v[188:191], v[120:123], v[12:15]
	v_mfma_f32_16x16x32_bf16 v[16:19], v[196:199], v[120:123], v[16:19]
	v_mfma_f32_16x16x32_bf16 v[20:23], v[204:207], v[120:123], v[20:23]
	v_mfma_f32_16x16x32_bf16 v[8:11], v[184:187], v[124:127], v[8:11]
	v_mfma_f32_16x16x32_bf16 v[12:15], v[192:195], v[124:127], v[12:15]
	v_mfma_f32_16x16x32_bf16 v[16:19], v[200:203], v[124:127], v[16:19]
	v_mfma_f32_16x16x32_bf16 v[20:23], v[208:211], v[124:127], v[20:23]
	s_mov_b32 s39, 4
